# A/B: per-cluster s_setprio 1/0 flips removed from the MLP-up and MLP-down GEMM k-loops
# baseline (speedup 1.0000x reference)
.LBB0_1140:
	s_add_u32 s18, s54, 0xfff80080
	s_addc_u32 s19, s55, -1
	s_add_i32 s73, 0, 0x10000
	s_cmp_eq_u32 s72, 28
	s_cselect_b32 s21, s9, s19
	s_cselect_b32 s20, s67, s18
	v_add_u32_e32 v138, s73, v141
	s_cselect_b32 s19, s7, s71
	s_cselect_b32 s18, s68, s70
	s_add_i32 s76, 0, 0x14000
	ds_read_b128 v[144:147], v138
	ds_read_b128 v[148:151], v138 offset:1024
	ds_read_b128 v[152:155], v138 offset:2048
	ds_read_b128 v[156:159], v138 offset:3072
	v_add_u32_e32 v138, s76, v141
	ds_read_b128 v[162:165], v138
	ds_read_b128 v[166:169], v138 offset:1024
	ds_read_b128 v[182:185], v138 offset:2048
	ds_read_b128 v[186:189], v138 offset:3072
	v_lshl_add_u64 v[138:139], s[54:55], 0, v[134:135]
	s_add_i32 m0, s58, 0xc000
	ds_read_b128 v[190:193], v143
	ds_read_b128 v[194:197], v143 offset:1024
	ds_read_b128 v[198:201], v143 offset:2048
	ds_read_b128 v[202:205], v143 offset:3072
	ds_read_b128 v[206:209], v143 offset:4096
	ds_read_b128 v[210:213], v143 offset:5120
	ds_read_b128 v[214:217], v143 offset:6144
	ds_read_b128 v[218:221], v143 offset:7168
	global_load_lds_dwordx4 v[138:139], off
	v_lshl_add_u64 v[138:139], s[54:55], 0, v[136:137]
	s_add_i32 m0, s58, 0xe000
	s_nop 0
	global_load_lds_dwordx4 v[138:139], off
	s_waitcnt vmcnt(8)
	s_waitcnt lgkmcnt(0)
	s_barrier
	s_waitcnt lgkmcnt(0)
	v_mfma_f32_16x16x32_bf16 v[124:127], v[144:147], v[190:193], v[124:127]
	v_mfma_f32_16x16x32_bf16 v[120:123], v[152:155], v[190:193], v[120:123]
	v_mfma_f32_16x16x32_bf16 v[108:111], v[144:147], v[198:201], v[108:111]
	v_mfma_f32_16x16x32_bf16 v[104:107], v[152:155], v[198:201], v[104:107]
	v_mfma_f32_16x16x32_bf16 v[92:95], v[144:147], v[206:209], v[92:95]
	v_mfma_f32_16x16x32_bf16 v[88:91], v[152:155], v[206:209], v[88:91]
	v_mfma_f32_16x16x32_bf16 v[76:79], v[144:147], v[214:217], v[76:79]
	v_mfma_f32_16x16x32_bf16 v[72:75], v[152:155], v[214:217], v[72:75]
	v_mfma_f32_16x16x32_bf16 v[124:127], v[148:151], v[194:197], v[124:127]
	v_mfma_f32_16x16x32_bf16 v[120:123], v[156:159], v[194:197], v[120:123]
	v_mfma_f32_16x16x32_bf16 v[108:111], v[148:151], v[202:205], v[108:111]
	v_mfma_f32_16x16x32_bf16 v[104:107], v[156:159], v[202:205], v[104:107]
	v_mfma_f32_16x16x32_bf16 v[92:95], v[148:151], v[210:213], v[92:95]
	v_mfma_f32_16x16x32_bf16 v[88:91], v[156:159], v[210:213], v[88:91]
	v_mfma_f32_16x16x32_bf16 v[76:79], v[148:151], v[218:221], v[76:79]
	v_mfma_f32_16x16x32_bf16 v[72:75], v[156:159], v[218:221], v[72:75]
	v_mfma_f32_16x16x32_bf16 v[116:119], v[162:165], v[190:193], v[116:119]
	v_mfma_f32_16x16x32_bf16 v[112:115], v[182:185], v[190:193], v[112:115]
	v_mfma_f32_16x16x32_bf16 v[100:103], v[162:165], v[198:201], v[100:103]
	v_mfma_f32_16x16x32_bf16 v[96:99], v[182:185], v[198:201], v[96:99]
	v_mfma_f32_16x16x32_bf16 v[84:87], v[162:165], v[206:209], v[84:87]
	v_mfma_f32_16x16x32_bf16 v[80:83], v[182:185], v[206:209], v[80:83]
	v_mfma_f32_16x16x32_bf16 v[68:71], v[162:165], v[214:217], v[68:71]
	v_mfma_f32_16x16x32_bf16 v[64:67], v[182:185], v[214:217], v[64:67]
	v_mfma_f32_16x16x32_bf16 v[116:119], v[166:169], v[194:197], v[116:119]
	v_mfma_f32_16x16x32_bf16 v[112:115], v[186:189], v[194:197], v[112:115]
	v_mfma_f32_16x16x32_bf16 v[100:103], v[166:169], v[202:205], v[100:103]
	v_mfma_f32_16x16x32_bf16 v[96:99], v[186:189], v[202:205], v[96:99]
	v_mfma_f32_16x16x32_bf16 v[84:87], v[166:169], v[210:213], v[84:87]
	v_mfma_f32_16x16x32_bf16 v[80:83], v[186:189], v[210:213], v[80:83]
	v_mfma_f32_16x16x32_bf16 v[68:71], v[166:169], v[218:221], v[68:71]
	v_mfma_f32_16x16x32_bf16 v[64:67], v[186:189], v[218:221], v[64:67]
	s_barrier
	s_add_i32 s73, s73, s51
	v_lshl_add_u64 v[138:139], s[18:19], 0, v[160:161]
	s_mov_b32 m0, s73
	ds_read_b128 v[190:193], v143 offset:16384
	ds_read_b128 v[194:197], v143 offset:17408
	ds_read_b128 v[198:201], v143 offset:18432
	ds_read_b128 v[202:205], v143 offset:19456
	ds_read_b128 v[206:209], v143 offset:20480
	ds_read_b128 v[210:213], v143 offset:21504
	ds_read_b128 v[214:217], v143 offset:22528
	ds_read_b128 v[218:221], v143 offset:23552
	global_load_lds_dwordx4 v[138:139], off
	s_add_i32 m0, s73, 0x2000
	s_add_u32 s74, s18, 0x80000
	v_lshl_add_u64 v[170:171], s[18:19], 0, v[128:129]
	s_addc_u32 s75, s19, 0
	s_add_i32 s73, s76, s51
	global_load_lds_dwordx4 v[170:171], off
	v_lshl_add_u64 v[222:223], s[74:75], 0, v[160:161]
	s_mov_b32 m0, s73
	v_lshl_add_u64 v[224:225], s[20:21], 0, v[130:131]
	global_load_lds_dwordx4 v[222:223], off
	v_lshl_add_u64 v[222:223], s[74:75], 0, v[128:129]
	s_add_i32 m0, s73, 0x2000
	s_nop 0
	global_load_lds_dwordx4 v[222:223], off
	v_lshl_add_u64 v[222:223], s[20:21], 0, v[132:133]
	s_mov_b32 m0, s58
	s_nop 0
	global_load_lds_dwordx4 v[222:223], off
	s_mov_b32 m0, s59
	s_nop 0
	global_load_lds_dwordx4 v[224:225], off
	s_waitcnt vmcnt(8)
	s_waitcnt lgkmcnt(0)
	s_barrier
	s_waitcnt lgkmcnt(0)
	v_mfma_f32_16x16x32_bf16 v[60:63], v[144:147], v[190:193], v[60:63]
	v_mfma_f32_16x16x32_bf16 v[56:59], v[152:155], v[190:193], v[56:59]
	v_mfma_f32_16x16x32_bf16 v[44:47], v[144:147], v[198:201], v[44:47]
	v_mfma_f32_16x16x32_bf16 v[40:43], v[152:155], v[198:201], v[40:43]
	v_mfma_f32_16x16x32_bf16 v[28:31], v[144:147], v[206:209], v[28:31]
	v_mfma_f32_16x16x32_bf16 v[24:27], v[152:155], v[206:209], v[24:27]
	v_mfma_f32_16x16x32_bf16 v[12:15], v[144:147], v[214:217], v[12:15]
	v_mfma_f32_16x16x32_bf16 v[8:11], v[152:155], v[214:217], v[8:11]
	v_mfma_f32_16x16x32_bf16 v[60:63], v[148:151], v[194:197], v[60:63]
	v_mfma_f32_16x16x32_bf16 v[56:59], v[156:159], v[194:197], v[56:59]
	v_mfma_f32_16x16x32_bf16 v[44:47], v[148:151], v[202:205], v[44:47]
	v_mfma_f32_16x16x32_bf16 v[40:43], v[156:159], v[202:205], v[40:43]
	v_mfma_f32_16x16x32_bf16 v[28:31], v[148:151], v[210:213], v[28:31]
	v_mfma_f32_16x16x32_bf16 v[24:27], v[156:159], v[210:213], v[24:27]
	v_mfma_f32_16x16x32_bf16 v[12:15], v[148:151], v[218:221], v[12:15]
	v_mfma_f32_16x16x32_bf16 v[8:11], v[156:159], v[218:221], v[8:11]
	v_mfma_f32_16x16x32_bf16 v[52:55], v[162:165], v[190:193], v[52:55]
	v_mfma_f32_16x16x32_bf16 v[48:51], v[182:185], v[190:193], v[48:51]
	v_mfma_f32_16x16x32_bf16 v[36:39], v[162:165], v[198:201], v[36:39]
	v_mfma_f32_16x16x32_bf16 v[32:35], v[182:185], v[198:201], v[32:35]
	v_mfma_f32_16x16x32_bf16 v[20:23], v[162:165], v[206:209], v[20:23]
	v_mfma_f32_16x16x32_bf16 v[16:19], v[182:185], v[206:209], v[16:19]
	v_mfma_f32_16x16x32_bf16 v[4:7], v[162:165], v[214:217], v[4:7]
	v_mfma_f32_16x16x32_bf16 v[0:3], v[182:185], v[214:217], v[0:3]
	v_mfma_f32_16x16x32_bf16 v[52:55], v[166:169], v[194:197], v[52:55]
	v_mfma_f32_16x16x32_bf16 v[48:51], v[186:189], v[194:197], v[48:51]
	v_mfma_f32_16x16x32_bf16 v[36:39], v[166:169], v[202:205], v[36:39]
	v_mfma_f32_16x16x32_bf16 v[32:35], v[186:189], v[202:205], v[32:35]
	v_mfma_f32_16x16x32_bf16 v[20:23], v[166:169], v[210:213], v[20:23]
	v_mfma_f32_16x16x32_bf16 v[16:19], v[186:189], v[210:213], v[16:19]
	v_mfma_f32_16x16x32_bf16 v[4:7], v[166:169], v[218:221], v[4:7]
	v_mfma_f32_16x16x32_bf16 v[0:3], v[186:189], v[218:221], v[0:3]
	s_barrier
	s_add_i32 s73, 0, 0x18000
	s_add_i32 s74, 0, 0x1c000
	v_add_u32_e32 v156, s73, v141
	v_add_u32_e32 v181, s74, v141
	ds_read_b128 v[144:147], v156
	ds_read_b128 v[148:151], v156 offset:1024
	ds_read_b128 v[152:155], v156 offset:2048
	ds_read_b128 v[156:159], v156 offset:3072
	ds_read_b128 v[162:165], v181
	ds_read_b128 v[166:169], v181 offset:1024
	ds_read_b128 v[182:185], v181 offset:2048
	ds_read_b128 v[186:189], v181 offset:3072
	s_add_u32 s20, s20, 0x80000
	s_addc_u32 s21, s21, 0
	s_mov_b32 m0, s60
	v_lshl_add_u64 v[226:227], s[20:21], 0, v[132:133]
	ds_read_b128 v[190:193], v143 offset:32768
	ds_read_b128 v[194:197], v143 offset:33792
	ds_read_b128 v[198:201], v143 offset:34816
	ds_read_b128 v[202:205], v143 offset:35840
	ds_read_b128 v[206:209], v143 offset:36864
	ds_read_b128 v[210:213], v143 offset:37888
	ds_read_b128 v[214:217], v143 offset:38912
	ds_read_b128 v[218:221], v143 offset:39936
	global_load_lds_dwordx4 v[226:227], off
	v_lshl_add_u64 v[226:227], s[20:21], 0, v[130:131]
	s_mov_b32 m0, s61
	s_nop 0
	global_load_lds_dwordx4 v[226:227], off
	s_waitcnt vmcnt(8)
	s_waitcnt lgkmcnt(0)
	s_barrier
	s_waitcnt lgkmcnt(0)
	v_mfma_f32_16x16x32_bf16 v[124:127], v[144:147], v[190:193], v[124:127]
	v_mfma_f32_16x16x32_bf16 v[120:123], v[152:155], v[190:193], v[120:123]
	v_mfma_f32_16x16x32_bf16 v[108:111], v[144:147], v[198:201], v[108:111]
	v_mfma_f32_16x16x32_bf16 v[104:107], v[152:155], v[198:201], v[104:107]
	v_mfma_f32_16x16x32_bf16 v[92:95], v[144:147], v[206:209], v[92:95]
	v_mfma_f32_16x16x32_bf16 v[88:91], v[152:155], v[206:209], v[88:91]
	v_mfma_f32_16x16x32_bf16 v[76:79], v[144:147], v[214:217], v[76:79]
	v_mfma_f32_16x16x32_bf16 v[72:75], v[152:155], v[214:217], v[72:75]
	v_mfma_f32_16x16x32_bf16 v[124:127], v[148:151], v[194:197], v[124:127]
	v_mfma_f32_16x16x32_bf16 v[120:123], v[156:159], v[194:197], v[120:123]
	v_mfma_f32_16x16x32_bf16 v[108:111], v[148:151], v[202:205], v[108:111]
	v_mfma_f32_16x16x32_bf16 v[104:107], v[156:159], v[202:205], v[104:107]
	v_mfma_f32_16x16x32_bf16 v[92:95], v[148:151], v[210:213], v[92:95]
	v_mfma_f32_16x16x32_bf16 v[88:91], v[156:159], v[210:213], v[88:91]
	v_mfma_f32_16x16x32_bf16 v[76:79], v[148:151], v[218:221], v[76:79]
	v_mfma_f32_16x16x32_bf16 v[72:75], v[156:159], v[218:221], v[72:75]
	v_mfma_f32_16x16x32_bf16 v[116:119], v[162:165], v[190:193], v[116:119]
	v_mfma_f32_16x16x32_bf16 v[112:115], v[182:185], v[190:193], v[112:115]
	v_mfma_f32_16x16x32_bf16 v[100:103], v[162:165], v[198:201], v[100:103]
	v_mfma_f32_16x16x32_bf16 v[96:99], v[182:185], v[198:201], v[96:99]
	v_mfma_f32_16x16x32_bf16 v[84:87], v[162:165], v[206:209], v[84:87]
	v_mfma_f32_16x16x32_bf16 v[80:83], v[182:185], v[206:209], v[80:83]
	v_mfma_f32_16x16x32_bf16 v[68:71], v[162:165], v[214:217], v[68:71]
	v_mfma_f32_16x16x32_bf16 v[64:67], v[182:185], v[214:217], v[64:67]
	v_mfma_f32_16x16x32_bf16 v[116:119], v[166:169], v[194:197], v[116:119]
	v_mfma_f32_16x16x32_bf16 v[112:115], v[186:189], v[194:197], v[112:115]
	v_mfma_f32_16x16x32_bf16 v[100:103], v[166:169], v[202:205], v[100:103]
	v_mfma_f32_16x16x32_bf16 v[96:99], v[186:189], v[202:205], v[96:99]
	v_mfma_f32_16x16x32_bf16 v[84:87], v[166:169], v[210:213], v[84:87]
	v_mfma_f32_16x16x32_bf16 v[80:83], v[186:189], v[210:213], v[80:83]
	v_mfma_f32_16x16x32_bf16 v[68:71], v[166:169], v[218:221], v[68:71]
	v_mfma_f32_16x16x32_bf16 v[64:67], v[186:189], v[218:221], v[64:67]
	s_barrier
	s_add_i32 s20, s73, s51
	v_lshl_add_u64 v[138:139], v[138:139], 0, s[64:65]
	s_mov_b32 m0, s20
	ds_read_b128 v[190:193], v143 offset:49152
	ds_read_b128 v[194:197], v143 offset:50176
	ds_read_b128 v[198:201], v143 offset:51200
	ds_read_b128 v[202:205], v143 offset:52224
	ds_read_b128 v[206:209], v143 offset:53248
	ds_read_b128 v[210:213], v143 offset:54272
	ds_read_b128 v[214:217], v143 offset:55296
	ds_read_b128 v[218:221], v143 offset:56320
	global_load_lds_dwordx4 v[138:139], off
	s_add_i32 m0, s20, 0x2000
	s_add_u32 s18, s18, 0x80080
	v_lshl_add_u64 v[138:139], v[170:171], 0, s[64:65]
	s_addc_u32 s19, s19, 0
	s_add_i32 s20, s74, s51
	global_load_lds_dwordx4 v[138:139], off
	v_lshl_add_u64 v[138:139], s[18:19], 0, v[160:161]
	s_mov_b32 m0, s20
	s_nop 0
	global_load_lds_dwordx4 v[138:139], off
	v_lshl_add_u64 v[138:139], s[18:19], 0, v[128:129]
	s_add_i32 m0, s20, 0x2000
	s_nop 0
	global_load_lds_dwordx4 v[138:139], off
	v_lshl_add_u64 v[138:139], v[222:223], 0, s[64:65]
	s_mov_b32 m0, s62
	s_nop 0
	global_load_lds_dwordx4 v[138:139], off
	v_lshl_add_u64 v[138:139], v[224:225], 0, s[64:65]
	s_mov_b32 m0, s63
	s_nop 0
	global_load_lds_dwordx4 v[138:139], off
	s_waitcnt vmcnt(8)
	s_waitcnt lgkmcnt(0)
	s_barrier
	s_waitcnt lgkmcnt(0)
	v_mfma_f32_16x16x32_bf16 v[60:63], v[144:147], v[190:193], v[60:63]
	v_mfma_f32_16x16x32_bf16 v[56:59], v[152:155], v[190:193], v[56:59]
	v_mfma_f32_16x16x32_bf16 v[44:47], v[144:147], v[198:201], v[44:47]
	v_mfma_f32_16x16x32_bf16 v[40:43], v[152:155], v[198:201], v[40:43]
	v_mfma_f32_16x16x32_bf16 v[28:31], v[144:147], v[206:209], v[28:31]
	v_mfma_f32_16x16x32_bf16 v[24:27], v[152:155], v[206:209], v[24:27]
	v_mfma_f32_16x16x32_bf16 v[12:15], v[144:147], v[214:217], v[12:15]
	v_mfma_f32_16x16x32_bf16 v[8:11], v[152:155], v[214:217], v[8:11]
	v_mfma_f32_16x16x32_bf16 v[60:63], v[148:151], v[194:197], v[60:63]
	v_mfma_f32_16x16x32_bf16 v[56:59], v[156:159], v[194:197], v[56:59]
	v_mfma_f32_16x16x32_bf16 v[44:47], v[148:151], v[202:205], v[44:47]
	v_mfma_f32_16x16x32_bf16 v[40:43], v[156:159], v[202:205], v[40:43]
	v_mfma_f32_16x16x32_bf16 v[28:31], v[148:151], v[210:213], v[28:31]
	v_mfma_f32_16x16x32_bf16 v[24:27], v[156:159], v[210:213], v[24:27]
	v_mfma_f32_16x16x32_bf16 v[12:15], v[148:151], v[218:221], v[12:15]
	v_mfma_f32_16x16x32_bf16 v[8:11], v[156:159], v[218:221], v[8:11]
	v_mfma_f32_16x16x32_bf16 v[52:55], v[162:165], v[190:193], v[52:55]
	v_mfma_f32_16x16x32_bf16 v[48:51], v[182:185], v[190:193], v[48:51]
	v_mfma_f32_16x16x32_bf16 v[36:39], v[162:165], v[198:201], v[36:39]
	v_mfma_f32_16x16x32_bf16 v[32:35], v[182:185], v[198:201], v[32:35]
	v_mfma_f32_16x16x32_bf16 v[20:23], v[162:165], v[206:209], v[20:23]
	v_mfma_f32_16x16x32_bf16 v[16:19], v[182:185], v[206:209], v[16:19]
	v_mfma_f32_16x16x32_bf16 v[4:7], v[162:165], v[214:217], v[4:7]
	v_mfma_f32_16x16x32_bf16 v[0:3], v[182:185], v[214:217], v[0:3]
	v_mfma_f32_16x16x32_bf16 v[52:55], v[166:169], v[194:197], v[52:55]
	v_mfma_f32_16x16x32_bf16 v[48:51], v[186:189], v[194:197], v[48:51]
	v_mfma_f32_16x16x32_bf16 v[36:39], v[166:169], v[202:205], v[36:39]
	v_mfma_f32_16x16x32_bf16 v[32:35], v[186:189], v[202:205], v[32:35]
	v_mfma_f32_16x16x32_bf16 v[20:23], v[166:169], v[210:213], v[20:23]
	v_mfma_f32_16x16x32_bf16 v[16:19], v[186:189], v[210:213], v[16:19]
	v_mfma_f32_16x16x32_bf16 v[4:7], v[166:169], v[218:221], v[4:7]
	v_mfma_f32_16x16x32_bf16 v[0:3], v[186:189], v[218:221], v[0:3]
	s_barrier
	s_add_i32 s72, s72, 2
	s_add_u32 s54, s54, 0x100
	s_addc_u32 s55, s55, 0
	s_add_u32 s70, s70, 0x100
	s_addc_u32 s71, s71, 0
	s_cmp_gt_u32 s72, 29
	s_cbranch_scc0 .LBB0_1140
	s_and_b64 vcc, exec, s[22:23]
	s_cbranch_vccz .LBB0_1143
	s_barrier

.LBB0_1235:
	s_add_i32 s23, s17, 2
	s_add_u32 s18, s76, 0xffe00080
	s_addc_u32 s19, s77, -1
	s_add_i32 s44, 0, 0x10000
	s_cmp_eq_u32 s0, s17
	s_cselect_b32 s21, s31, s19
	s_cselect_b32 s20, s30, s18
	s_cselect_b32 s19, s55, s15
	s_cselect_b32 s18, s54, s1
	s_add_i32 s17, 0, 0x14000
	v_add_u32_e32 v108, s44, v181
	v_add_u32_e32 v192, s17, v181
	ds_read_b128 v[96:99], v108
	ds_read_b128 v[100:103], v108 offset:1024
	ds_read_b128 v[104:107], v108 offset:2048
	ds_read_b128 v[108:111], v108 offset:3072
	ds_read_b128 v[168:171], v192
	ds_read_b128 v[184:187], v192 offset:1024
	ds_read_b128 v[188:191], v192 offset:2048
	ds_read_b128 v[192:195], v192 offset:3072
	v_lshl_add_u64 v[228:229], s[76:77], 0, v[164:165]
	s_add_i32 m0, s58, 0xc000
	ds_read_b128 v[196:199], v183
	ds_read_b128 v[200:203], v183 offset:1024
	ds_read_b128 v[204:207], v183 offset:2048
	ds_read_b128 v[208:211], v183 offset:3072
	ds_read_b128 v[212:215], v183 offset:4096
	ds_read_b128 v[216:219], v183 offset:5120
	ds_read_b128 v[220:223], v183 offset:6144
	ds_read_b128 v[224:227], v183 offset:7168
	global_load_lds_dwordx4 v[228:229], off
	v_lshl_add_u64 v[228:229], s[76:77], 0, v[166:167]
	s_add_i32 m0, s58, 0xe000
	s_nop 0
	global_load_lds_dwordx4 v[228:229], off
	s_waitcnt vmcnt(8)
	s_waitcnt lgkmcnt(0)
	s_barrier
	s_waitcnt lgkmcnt(0)
	v_mfma_f32_16x16x32_bf16 v[140:143], v[96:99], v[196:199], v[140:143]
	v_mfma_f32_16x16x32_bf16 v[136:139], v[104:107], v[196:199], v[136:139]
	v_mfma_f32_16x16x32_bf16 v[132:135], v[96:99], v[204:207], v[132:135]
	v_mfma_f32_16x16x32_bf16 v[128:131], v[104:107], v[204:207], v[128:131]
	v_mfma_f32_16x16x32_bf16 v[92:95], v[96:99], v[212:215], v[92:95]
	v_mfma_f32_16x16x32_bf16 v[88:91], v[104:107], v[212:215], v[88:91]
	v_mfma_f32_16x16x32_bf16 v[84:87], v[96:99], v[220:223], v[84:87]
	v_mfma_f32_16x16x32_bf16 v[80:83], v[104:107], v[220:223], v[80:83]
	v_mfma_f32_16x16x32_bf16 v[140:143], v[100:103], v[200:203], v[140:143]
	v_mfma_f32_16x16x32_bf16 v[136:139], v[108:111], v[200:203], v[136:139]
	v_mfma_f32_16x16x32_bf16 v[132:135], v[100:103], v[208:211], v[132:135]
	v_mfma_f32_16x16x32_bf16 v[128:131], v[108:111], v[208:211], v[128:131]
	v_mfma_f32_16x16x32_bf16 v[92:95], v[100:103], v[216:219], v[92:95]
	v_mfma_f32_16x16x32_bf16 v[88:91], v[108:111], v[216:219], v[88:91]
	v_mfma_f32_16x16x32_bf16 v[84:87], v[100:103], v[224:227], v[84:87]
	v_mfma_f32_16x16x32_bf16 v[80:83], v[108:111], v[224:227], v[80:83]
	v_mfma_f32_16x16x32_bf16 v[124:127], v[168:171], v[196:199], v[124:127]
	v_mfma_f32_16x16x32_bf16 v[120:123], v[188:191], v[196:199], v[120:123]
	v_mfma_f32_16x16x32_bf16 v[116:119], v[168:171], v[204:207], v[116:119]
	v_mfma_f32_16x16x32_bf16 v[112:115], v[188:191], v[204:207], v[112:115]
	v_mfma_f32_16x16x32_bf16 v[76:79], v[168:171], v[212:215], v[76:79]
	v_mfma_f32_16x16x32_bf16 v[72:75], v[188:191], v[212:215], v[72:75]
	v_mfma_f32_16x16x32_bf16 v[68:71], v[168:171], v[220:223], v[68:71]
	v_mfma_f32_16x16x32_bf16 v[64:67], v[188:191], v[220:223], v[64:67]
	v_mfma_f32_16x16x32_bf16 v[124:127], v[184:187], v[200:203], v[124:127]
	v_mfma_f32_16x16x32_bf16 v[120:123], v[192:195], v[200:203], v[120:123]
	v_mfma_f32_16x16x32_bf16 v[116:119], v[184:187], v[208:211], v[116:119]
	v_mfma_f32_16x16x32_bf16 v[112:115], v[192:195], v[208:211], v[112:115]
	v_mfma_f32_16x16x32_bf16 v[76:79], v[184:187], v[216:219], v[76:79]
	v_mfma_f32_16x16x32_bf16 v[72:75], v[192:195], v[216:219], v[72:75]
	v_mfma_f32_16x16x32_bf16 v[68:71], v[184:187], v[224:227], v[68:71]
	v_mfma_f32_16x16x32_bf16 v[64:67], v[192:195], v[224:227], v[64:67]
	s_barrier
	s_add_i32 s44, s44, s51
	v_lshl_add_u64 v[228:229], s[18:19], 0, v[160:161]
	s_mov_b32 m0, s44
	ds_read_b128 v[196:199], v183 offset:16384
	ds_read_b128 v[200:203], v183 offset:17408
	ds_read_b128 v[204:207], v183 offset:18432
	ds_read_b128 v[208:211], v183 offset:19456
	ds_read_b128 v[212:215], v183 offset:20480
	ds_read_b128 v[216:219], v183 offset:21504
	ds_read_b128 v[220:223], v183 offset:22528
	ds_read_b128 v[224:227], v183 offset:23552
	global_load_lds_dwordx4 v[228:229], off
	s_add_i32 m0, s44, 0x2000
	s_add_u32 s44, s18, 0x200000
	v_lshl_add_u64 v[230:231], s[18:19], 0, v[144:145]
	s_addc_u32 s45, s19, 0
	s_add_i32 s17, s17, s51
	global_load_lds_dwordx4 v[230:231], off
	v_lshl_add_u64 v[232:233], s[44:45], 0, v[160:161]
	s_mov_b32 m0, s17
	v_lshl_add_u64 v[234:235], s[20:21], 0, v[144:145]
	global_load_lds_dwordx4 v[232:233], off
	v_lshl_add_u64 v[232:233], s[44:45], 0, v[144:145]
	s_add_i32 m0, s17, 0x2000
	s_nop 0
	global_load_lds_dwordx4 v[232:233], off
	v_lshl_add_u64 v[232:233], s[20:21], 0, v[160:161]
	s_mov_b32 m0, s58
	s_nop 0
	global_load_lds_dwordx4 v[232:233], off
	s_mov_b32 m0, s59
	s_nop 0
	global_load_lds_dwordx4 v[234:235], off
	s_waitcnt vmcnt(8)
	s_waitcnt lgkmcnt(0)
	s_barrier
	s_waitcnt lgkmcnt(0)
	v_mfma_f32_16x16x32_bf16 v[60:63], v[96:99], v[196:199], v[60:63]
	v_mfma_f32_16x16x32_bf16 v[56:59], v[104:107], v[196:199], v[56:59]
	v_mfma_f32_16x16x32_bf16 v[52:55], v[96:99], v[204:207], v[52:55]
	v_mfma_f32_16x16x32_bf16 v[48:51], v[104:107], v[204:207], v[48:51]
	v_mfma_f32_16x16x32_bf16 v[28:31], v[96:99], v[212:215], v[28:31]
	v_mfma_f32_16x16x32_bf16 v[24:27], v[104:107], v[212:215], v[24:27]
	v_mfma_f32_16x16x32_bf16 v[12:15], v[96:99], v[220:223], v[12:15]
	v_mfma_f32_16x16x32_bf16 v[8:11], v[104:107], v[220:223], v[8:11]
	v_mfma_f32_16x16x32_bf16 v[60:63], v[100:103], v[200:203], v[60:63]
	v_mfma_f32_16x16x32_bf16 v[56:59], v[108:111], v[200:203], v[56:59]
	v_mfma_f32_16x16x32_bf16 v[52:55], v[100:103], v[208:211], v[52:55]
	v_mfma_f32_16x16x32_bf16 v[48:51], v[108:111], v[208:211], v[48:51]
	v_mfma_f32_16x16x32_bf16 v[28:31], v[100:103], v[216:219], v[28:31]
	v_mfma_f32_16x16x32_bf16 v[24:27], v[108:111], v[216:219], v[24:27]
	v_mfma_f32_16x16x32_bf16 v[12:15], v[100:103], v[224:227], v[12:15]
	v_mfma_f32_16x16x32_bf16 v[8:11], v[108:111], v[224:227], v[8:11]
	v_mfma_f32_16x16x32_bf16 v[44:47], v[168:171], v[196:199], v[44:47]
	v_mfma_f32_16x16x32_bf16 v[40:43], v[188:191], v[196:199], v[40:43]
	v_mfma_f32_16x16x32_bf16 v[36:39], v[168:171], v[204:207], v[36:39]
	v_mfma_f32_16x16x32_bf16 v[32:35], v[188:191], v[204:207], v[32:35]
	v_mfma_f32_16x16x32_bf16 v[20:23], v[168:171], v[212:215], v[20:23]
	v_mfma_f32_16x16x32_bf16 v[16:19], v[188:191], v[212:215], v[16:19]
	v_mfma_f32_16x16x32_bf16 v[4:7], v[168:171], v[220:223], v[4:7]
	v_mfma_f32_16x16x32_bf16 v[0:3], v[188:191], v[220:223], v[0:3]
	v_mfma_f32_16x16x32_bf16 v[44:47], v[184:187], v[200:203], v[44:47]
	v_mfma_f32_16x16x32_bf16 v[40:43], v[192:195], v[200:203], v[40:43]
	v_mfma_f32_16x16x32_bf16 v[36:39], v[184:187], v[208:211], v[36:39]
	v_mfma_f32_16x16x32_bf16 v[32:35], v[192:195], v[208:211], v[32:35]
	v_mfma_f32_16x16x32_bf16 v[20:23], v[184:187], v[216:219], v[20:23]
	v_mfma_f32_16x16x32_bf16 v[16:19], v[192:195], v[216:219], v[16:19]
	v_mfma_f32_16x16x32_bf16 v[4:7], v[184:187], v[224:227], v[4:7]
	v_mfma_f32_16x16x32_bf16 v[0:3], v[192:195], v[224:227], v[0:3]
	s_barrier
	s_add_i32 s17, 0, 0x18000
	s_add_i32 s44, 0, 0x1c000
	v_add_u32_e32 v108, s17, v181
	v_add_u32_e32 v192, s44, v181
	ds_read_b128 v[96:99], v108
	ds_read_b128 v[100:103], v108 offset:1024
	ds_read_b128 v[104:107], v108 offset:2048
	ds_read_b128 v[108:111], v108 offset:3072
	ds_read_b128 v[168:171], v192
	ds_read_b128 v[184:187], v192 offset:1024
	ds_read_b128 v[188:191], v192 offset:2048
	ds_read_b128 v[192:195], v192 offset:3072
	s_add_u32 s20, s20, 0x200000
	s_addc_u32 s21, s21, 0
	s_mov_b32 m0, s60
	v_lshl_add_u64 v[236:237], s[20:21], 0, v[160:161]
	ds_read_b128 v[196:199], v183 offset:32768
	ds_read_b128 v[200:203], v183 offset:33792
	ds_read_b128 v[204:207], v183 offset:34816
	ds_read_b128 v[208:211], v183 offset:35840
	ds_read_b128 v[212:215], v183 offset:36864
	ds_read_b128 v[216:219], v183 offset:37888
	ds_read_b128 v[220:223], v183 offset:38912
	ds_read_b128 v[224:227], v183 offset:39936
	global_load_lds_dwordx4 v[236:237], off
	v_lshl_add_u64 v[236:237], s[20:21], 0, v[144:145]
	s_mov_b32 m0, s61
	s_nop 0
	global_load_lds_dwordx4 v[236:237], off
	s_waitcnt vmcnt(8)
	s_waitcnt lgkmcnt(0)
	s_barrier
	s_waitcnt lgkmcnt(0)
	v_mfma_f32_16x16x32_bf16 v[140:143], v[96:99], v[196:199], v[140:143]
	v_mfma_f32_16x16x32_bf16 v[136:139], v[104:107], v[196:199], v[136:139]
	v_mfma_f32_16x16x32_bf16 v[132:135], v[96:99], v[204:207], v[132:135]
	v_mfma_f32_16x16x32_bf16 v[128:131], v[104:107], v[204:207], v[128:131]
	v_mfma_f32_16x16x32_bf16 v[92:95], v[96:99], v[212:215], v[92:95]
	v_mfma_f32_16x16x32_bf16 v[88:91], v[104:107], v[212:215], v[88:91]
	v_mfma_f32_16x16x32_bf16 v[84:87], v[96:99], v[220:223], v[84:87]
	v_mfma_f32_16x16x32_bf16 v[80:83], v[104:107], v[220:223], v[80:83]
	v_mfma_f32_16x16x32_bf16 v[140:143], v[100:103], v[200:203], v[140:143]
	v_mfma_f32_16x16x32_bf16 v[136:139], v[108:111], v[200:203], v[136:139]
	v_mfma_f32_16x16x32_bf16 v[132:135], v[100:103], v[208:211], v[132:135]
	v_mfma_f32_16x16x32_bf16 v[128:131], v[108:111], v[208:211], v[128:131]
	v_mfma_f32_16x16x32_bf16 v[92:95], v[100:103], v[216:219], v[92:95]
	v_mfma_f32_16x16x32_bf16 v[88:91], v[108:111], v[216:219], v[88:91]
	v_mfma_f32_16x16x32_bf16 v[84:87], v[100:103], v[224:227], v[84:87]
	v_mfma_f32_16x16x32_bf16 v[80:83], v[108:111], v[224:227], v[80:83]
	v_mfma_f32_16x16x32_bf16 v[124:127], v[168:171], v[196:199], v[124:127]
	v_mfma_f32_16x16x32_bf16 v[120:123], v[188:191], v[196:199], v[120:123]
	v_mfma_f32_16x16x32_bf16 v[116:119], v[168:171], v[204:207], v[116:119]
	v_mfma_f32_16x16x32_bf16 v[112:115], v[188:191], v[204:207], v[112:115]
	v_mfma_f32_16x16x32_bf16 v[76:79], v[168:171], v[212:215], v[76:79]
	v_mfma_f32_16x16x32_bf16 v[72:75], v[188:191], v[212:215], v[72:75]
	v_mfma_f32_16x16x32_bf16 v[68:71], v[168:171], v[220:223], v[68:71]
	v_mfma_f32_16x16x32_bf16 v[64:67], v[188:191], v[220:223], v[64:67]
	v_mfma_f32_16x16x32_bf16 v[124:127], v[184:187], v[200:203], v[124:127]
	v_mfma_f32_16x16x32_bf16 v[120:123], v[192:195], v[200:203], v[120:123]
	v_mfma_f32_16x16x32_bf16 v[116:119], v[184:187], v[208:211], v[116:119]
	v_mfma_f32_16x16x32_bf16 v[112:115], v[192:195], v[208:211], v[112:115]
	v_mfma_f32_16x16x32_bf16 v[76:79], v[184:187], v[216:219], v[76:79]
	v_mfma_f32_16x16x32_bf16 v[72:75], v[192:195], v[216:219], v[72:75]
	v_mfma_f32_16x16x32_bf16 v[68:71], v[184:187], v[224:227], v[68:71]
	v_mfma_f32_16x16x32_bf16 v[64:67], v[192:195], v[224:227], v[64:67]
	s_barrier
	s_add_i32 s17, s17, s51
	v_lshl_add_u64 v[228:229], v[228:229], 0, s[64:65]
	s_mov_b32 m0, s17
	ds_read_b128 v[196:199], v183 offset:49152
	ds_read_b128 v[200:203], v183 offset:50176
	ds_read_b128 v[204:207], v183 offset:51200
	ds_read_b128 v[208:211], v183 offset:52224
	ds_read_b128 v[212:215], v183 offset:53248
	ds_read_b128 v[216:219], v183 offset:54272
	ds_read_b128 v[220:223], v183 offset:55296
	ds_read_b128 v[224:227], v183 offset:56320
	global_load_lds_dwordx4 v[228:229], off
	s_add_i32 m0, s17, 0x2000
	s_add_u32 s18, s18, 0x200080
	v_lshl_add_u64 v[228:229], v[230:231], 0, s[64:65]
	s_addc_u32 s19, s19, 0
	s_add_i32 s17, s44, s51
	global_load_lds_dwordx4 v[228:229], off
	v_lshl_add_u64 v[228:229], s[18:19], 0, v[160:161]
	s_mov_b32 m0, s17
	s_nop 0
	global_load_lds_dwordx4 v[228:229], off
	v_lshl_add_u64 v[228:229], s[18:19], 0, v[144:145]
	s_add_i32 m0, s17, 0x2000
	s_nop 0
	global_load_lds_dwordx4 v[228:229], off
	v_lshl_add_u64 v[228:229], v[232:233], 0, s[64:65]
	s_mov_b32 m0, s66
	s_nop 0
	global_load_lds_dwordx4 v[228:229], off
	v_lshl_add_u64 v[228:229], v[234:235], 0, s[64:65]
	s_mov_b32 m0, s67
	s_nop 0
	global_load_lds_dwordx4 v[228:229], off
	s_waitcnt vmcnt(8)
	s_waitcnt lgkmcnt(0)
	s_barrier
	s_waitcnt lgkmcnt(0)
	v_mfma_f32_16x16x32_bf16 v[60:63], v[96:99], v[196:199], v[60:63]
	v_mfma_f32_16x16x32_bf16 v[56:59], v[104:107], v[196:199], v[56:59]
	v_mfma_f32_16x16x32_bf16 v[52:55], v[96:99], v[204:207], v[52:55]
	v_mfma_f32_16x16x32_bf16 v[48:51], v[104:107], v[204:207], v[48:51]
	v_mfma_f32_16x16x32_bf16 v[28:31], v[96:99], v[212:215], v[28:31]
	v_mfma_f32_16x16x32_bf16 v[24:27], v[104:107], v[212:215], v[24:27]
	v_mfma_f32_16x16x32_bf16 v[12:15], v[96:99], v[220:223], v[12:15]
	v_mfma_f32_16x16x32_bf16 v[8:11], v[104:107], v[220:223], v[8:11]
	v_mfma_f32_16x16x32_bf16 v[60:63], v[100:103], v[200:203], v[60:63]
	v_mfma_f32_16x16x32_bf16 v[56:59], v[108:111], v[200:203], v[56:59]
	v_mfma_f32_16x16x32_bf16 v[52:55], v[100:103], v[208:211], v[52:55]
	v_mfma_f32_16x16x32_bf16 v[48:51], v[108:111], v[208:211], v[48:51]
	v_mfma_f32_16x16x32_bf16 v[28:31], v[100:103], v[216:219], v[28:31]
	v_mfma_f32_16x16x32_bf16 v[24:27], v[108:111], v[216:219], v[24:27]
	v_mfma_f32_16x16x32_bf16 v[12:15], v[100:103], v[224:227], v[12:15]
	v_mfma_f32_16x16x32_bf16 v[8:11], v[108:111], v[224:227], v[8:11]
	v_mfma_f32_16x16x32_bf16 v[44:47], v[168:171], v[196:199], v[44:47]
	v_mfma_f32_16x16x32_bf16 v[40:43], v[188:191], v[196:199], v[40:43]
	v_mfma_f32_16x16x32_bf16 v[36:39], v[168:171], v[204:207], v[36:39]
	v_mfma_f32_16x16x32_bf16 v[32:35], v[188:191], v[204:207], v[32:35]
	v_mfma_f32_16x16x32_bf16 v[20:23], v[168:171], v[212:215], v[20:23]
	v_mfma_f32_16x16x32_bf16 v[16:19], v[188:191], v[212:215], v[16:19]
	v_mfma_f32_16x16x32_bf16 v[4:7], v[168:171], v[220:223], v[4:7]
	v_mfma_f32_16x16x32_bf16 v[0:3], v[188:191], v[220:223], v[0:3]
	v_mfma_f32_16x16x32_bf16 v[44:47], v[184:187], v[200:203], v[44:47]
	v_mfma_f32_16x16x32_bf16 v[40:43], v[192:195], v[200:203], v[40:43]
	v_mfma_f32_16x16x32_bf16 v[36:39], v[184:187], v[208:211], v[36:39]
	v_mfma_f32_16x16x32_bf16 v[32:35], v[192:195], v[208:211], v[32:35]
	v_mfma_f32_16x16x32_bf16 v[20:23], v[184:187], v[216:219], v[20:23]
	v_mfma_f32_16x16x32_bf16 v[16:19], v[192:195], v[216:219], v[16:19]
	v_mfma_f32_16x16x32_bf16 v[4:7], v[184:187], v[224:227], v[4:7]
	v_mfma_f32_16x16x32_bf16 v[0:3], v[192:195], v[224:227], v[0:3]
	s_barrier
	s_add_u32 s76, s76, 0x100
	s_addc_u32 s77, s77, 0
	s_add_u32 s1, s1, 0x100
	s_addc_u32 s15, s15, 0
	s_cmp_ge_u32 s23, s14
	s_mov_b32 s17, s23
	s_cbranch_scc0 .LBB0_1235
	s_and_b64 vcc, exec, s[10:11]
	s_cbranch_vccz .LBB0_1238
	s_barrier
